# hand-written parallel fill_rowscales in the 4 FFN-in phases (all loads in flight, 512 threads)
# speedup vs baseline: 1.0033x; 1.0033x over previous
; #define LAS __attribute__((address_space(3)))
;     __host__ __device__ bool next(int i, Unit& u) const {
;         const long L = (long)i * G + c; if (L >= nwg) return false;
;         int wgid = (int)L; { const int q = nwg / NXCD, r = nwg % NXCD, xcd = wgid % NXCD, off = wgid / NXCD; wgid = (xcd < r ? xcd * (q + 1) : r * (q + 1) + (xcd - r) * q) + off; }
;         const int nig = WGM * nN, gid = wgid / nig, fm = gid * WGM, gsz = (nM - fm) < WGM ? (nM - fm) : WGM;
;         u.pm = fm + ((wgid % nig) % gsz); u.pn = (wgid % nig) / gsz; return true;
;     }
; __device__ __forceinline__ u32x4 pk8(const f32x4 a, const f32x4 b) { u32x4 w; w.x = pk2(a[0], a[1]); w.y = pk2(a[2], a[3]); w.z = pk2(b[0], b[1]); w.w = pk2(b[2], b[3]); return w; }
; __device__ __forceinline__ float rowscale(const float* SS, int row) {
;     const f32x4* p = (const f32x4*)(SS + (size_t)row * 16);
;     const f32x4 a = p[0], b = p[1], c = p[2], d = p[3];
;     const float s = ((a[0] + a[1]) + (a[2] + a[3])) + ((b[0] + b[1]) + (b[2] + b[3])) + ((c[0] + c[1]) + (c[2] + c[3])) + ((d[0] + d[1]) + (d[2] + d[3]));
;     return 1.0f / sqrtf(s * (1.0f / 1024.0f) + 1e-6f);
; }
; DI void fill_rowscales(const pg8::StaticOrder& S, const float* SS, LAS float* rs, int bycol) {
;     pg8::Unit u;
;     for (int ui = 0; ui < RS_SLOTS && S.next(ui, u); ++ui) {
;         const int t = threadIdx.x;
;         if (t < 256) rs[ui * 256 + t] = pg8::rowscale(SS, (bycol ? u.pn : u.pm) * 256 + t);
;     }
.LBB0_322:
	s_add_u32 s6, s90, 0x5900000
	s_waitcnt vmcnt(23)
	v_lshlrev_b32_e32 v8, 2, v254
	s_addc_u32 s7, s91, 0
	s_ashr_i32 s3, s2, 31
	s_movk_i32 s0, 0x100
	v_add_u32_e32 v0, 0, v8
	s_ashr_i32 s30, s94, 31
	s_mov_b32 s31, s94
	v_cmp_gt_u32_e64 s[0:1], s0, v254
	v_add_u32_e32 v2, 0x20000, v0
	s_movk_i32 s14, 0xd000
	v_mov_b64_e32 v[0:1], 0xaff
	s_movk_i32 s15, 0x161
	v_mov_b32_e32 v3, 0x358637bd
	s_mov_b32 s16, 0xf800000
	v_mov_b32_e32 v4, 0x260
	s_mov_b64 s[8:9], s[2:3]
	v_readfirstlane_b32 s12, v254
	v_and_b32_e32 v5, 0xff, v254
	s_nop 3
	s_lshr_b32 s12, s12, 8
	s_mul_i32 s13, s12, s31
	s_add_i32 s8, s2, s13
	s_lshl_b32 s9, s31, 1
	s_cmp_lt_u32 s8, 0xb00
	s_cselect_b32 s4, s8, s2
	s_and_b32 s5, s4, 7
	s_lshr_b32 s4, s4, 3
	s_mul_i32 s5, s5, 0x160
	s_add_i32 s4, s4, s5
	s_mul_hi_u32 s5, s4, 0x1745d18
	s_mul_i32 s13, s5, 0xb0
	s_sub_i32 s13, s4, s13
	s_and_b32 s13, s13, 7
	s_lshl_b32 s5, s5, 3
	s_add_i32 s5, s5, s13
	v_lshl_or_b32 v26, s5, 8, v5
	v_lshlrev_b32_e32 v26, 6, v26
	s_add_i32 s8, s8, s9
	global_load_dwordx4 v[32:35], v26, s[6:7]
	global_load_dwordx4 v[36:39], v26, s[6:7] offset:16
	global_load_dwordx4 v[40:43], v26, s[6:7] offset:32
	global_load_dwordx4 v[44:47], v26, s[6:7] offset:48
	s_cmp_lt_u32 s8, 0xb00
	s_cselect_b32 s4, s8, s2
	s_and_b32 s5, s4, 7
	s_lshr_b32 s4, s4, 3
	s_mul_i32 s5, s5, 0x160
	s_add_i32 s4, s4, s5
	s_mul_hi_u32 s5, s4, 0x1745d18
	s_mul_i32 s13, s5, 0xb0
	s_sub_i32 s13, s4, s13
	s_and_b32 s13, s13, 7
	s_lshl_b32 s5, s5, 3
	s_add_i32 s5, s5, s13
	v_lshl_or_b32 v27, s5, 8, v5
	v_lshlrev_b32_e32 v27, 6, v27
	s_add_i32 s8, s8, s9
	global_load_dwordx4 v[48:51], v27, s[6:7]
	global_load_dwordx4 v[52:55], v27, s[6:7] offset:16
	global_load_dwordx4 v[56:59], v27, s[6:7] offset:32
	global_load_dwordx4 v[60:63], v27, s[6:7] offset:48
	s_cmp_lt_u32 s8, 0xb00
	s_cselect_b32 s4, s8, s2
	s_and_b32 s5, s4, 7
	s_lshr_b32 s4, s4, 3
	s_mul_i32 s5, s5, 0x160
	s_add_i32 s4, s4, s5
	s_mul_hi_u32 s5, s4, 0x1745d18
	s_mul_i32 s13, s5, 0xb0
	s_sub_i32 s13, s4, s13
	s_and_b32 s13, s13, 7
	s_lshl_b32 s5, s5, 3
	s_add_i32 s5, s5, s13
	v_lshl_or_b32 v28, s5, 8, v5
	v_lshlrev_b32_e32 v28, 6, v28
	s_add_i32 s8, s8, s9
	global_load_dwordx4 v[64:67], v28, s[6:7]
	global_load_dwordx4 v[68:71], v28, s[6:7] offset:16
	global_load_dwordx4 v[72:75], v28, s[6:7] offset:32
	global_load_dwordx4 v[76:79], v28, s[6:7] offset:48
	s_cmp_lt_u32 s8, 0xb00
	s_cselect_b32 s4, s8, s2
	s_and_b32 s5, s4, 7
	s_lshr_b32 s4, s4, 3
	s_mul_i32 s5, s5, 0x160
	s_add_i32 s4, s4, s5
	s_mul_hi_u32 s5, s4, 0x1745d18
	s_mul_i32 s13, s5, 0xb0
	s_sub_i32 s13, s4, s13
	s_and_b32 s13, s13, 7
	s_lshl_b32 s5, s5, 3
	s_add_i32 s5, s5, s13
	v_lshl_or_b32 v29, s5, 8, v5
	v_lshlrev_b32_e32 v29, 6, v29
	s_add_i32 s8, s8, s9
	global_load_dwordx4 v[80:83], v29, s[6:7]
	global_load_dwordx4 v[84:87], v29, s[6:7] offset:16
	global_load_dwordx4 v[88:91], v29, s[6:7] offset:32
	global_load_dwordx4 v[92:95], v29, s[6:7] offset:48
	s_cmp_lt_u32 s8, 0xb00
	s_cselect_b32 s4, s8, s2
	s_and_b32 s5, s4, 7
	s_lshr_b32 s4, s4, 3
	s_mul_i32 s5, s5, 0x160
	s_add_i32 s4, s4, s5
	s_mul_hi_u32 s5, s4, 0x1745d18
	s_mul_i32 s13, s5, 0xb0
	s_sub_i32 s13, s4, s13
	s_and_b32 s13, s13, 7
	s_lshl_b32 s5, s5, 3
	s_add_i32 s5, s5, s13
	v_lshl_or_b32 v30, s5, 8, v5
	v_lshlrev_b32_e32 v30, 6, v30
	s_add_i32 s8, s8, s9
	global_load_dwordx4 v[96:99], v30, s[6:7]
	global_load_dwordx4 v[100:103], v30, s[6:7] offset:16
	global_load_dwordx4 v[104:107], v30, s[6:7] offset:32
	global_load_dwordx4 v[108:111], v30, s[6:7] offset:48
	s_cmp_lt_u32 s8, 0xb00
	s_cselect_b32 s4, s8, s2
	s_and_b32 s5, s4, 7
	s_lshr_b32 s4, s4, 3
	s_mul_i32 s5, s5, 0x160
	s_add_i32 s4, s4, s5
	s_mul_hi_u32 s5, s4, 0x1745d18
	s_mul_i32 s13, s5, 0xb0
	s_sub_i32 s13, s4, s13
	s_and_b32 s13, s13, 7
	s_lshl_b32 s5, s5, 3
	s_add_i32 s5, s5, s13
	v_lshl_or_b32 v31, s5, 8, v5
	v_lshlrev_b32_e32 v31, 6, v31
	s_add_i32 s8, s8, s9
	global_load_dwordx4 v[112:115], v31, s[6:7]
	global_load_dwordx4 v[116:119], v31, s[6:7] offset:16
	global_load_dwordx4 v[120:123], v31, s[6:7] offset:32
	global_load_dwordx4 v[124:127], v31, s[6:7] offset:48
	s_waitcnt vmcnt(20)
	v_add_f32_e32 v9, v32, v33
	v_add_f32_e32 v13, v34, v35
	v_add_f32_e32 v9, v9, v13
	v_add_f32_e32 v10, v36, v37
	v_add_f32_e32 v13, v38, v39
	v_add_f32_e32 v10, v10, v13
	v_add_f32_e32 v11, v40, v41
	v_add_f32_e32 v13, v42, v43
	v_add_f32_e32 v11, v11, v13
	v_add_f32_e32 v12, v44, v45
	v_add_f32_e32 v13, v46, v47
	v_add_f32_e32 v12, v12, v13
	v_add_f32_e32 v9, v9, v10
	v_add_f32_e32 v9, v9, v11
	v_add_f32_e32 v9, v9, v12
	v_fmamk_f32 v9, v9, 0x3a800000, v3
	v_mul_f32_e32 v10, 0x4f800000, v9
	v_cmp_gt_f32_e32 vcc, s16, v9
	s_nop 1
	v_cndmask_b32_e32 v9, v9, v10, vcc
	v_sqrt_f32_e32 v10, v9
	s_nop 0
	v_add_u32_e32 v11, -1, v10
	v_add_u32_e32 v12, 1, v10
	v_fma_f32 v13, -v11, v10, v9
	v_fma_f32 v14, -v12, v10, v9
	v_cmp_ge_f32_e64 s[4:5], 0, v13
	s_nop 1
	v_cndmask_b32_e64 v10, v10, v11, s[4:5]
	v_cmp_lt_f32_e64 s[4:5], 0, v14
	s_nop 1
	v_cndmask_b32_e64 v10, v10, v12, s[4:5]
	v_mul_f32_e32 v11, 0x37800000, v10
	v_cndmask_b32_e32 v10, v10, v11, vcc
	v_cmp_class_f32_e32 vcc, v9, v4
	s_nop 1
	v_cndmask_b32_e32 v9, v10, v9, vcc
	v_div_scale_f32 v10, s[4:5], v9, v9, 1.0
	v_rcp_f32_e32 v11, v10
	v_div_scale_f32 v12, vcc, 1.0, v9, 1.0
	v_fma_f32 v13, -v10, v11, 1.0
	v_fmac_f32_e32 v11, v13, v11
	v_mul_f32_e32 v13, v12, v11
	v_fma_f32 v14, -v10, v13, v12
	v_fmac_f32_e32 v13, v14, v11
	v_fma_f32 v10, -v10, v13, v12
	v_div_fmas_f32 v10, v10, v11, v13
	v_div_fixup_f32 v9, v10, v9, 1.0
	ds_write_b32 v2, v9
	s_waitcnt vmcnt(16)
; #define LAS __attribute__((address_space(3)))
; __device__ __forceinline__ float rowscale(const float* SS, int row) {
;     const f32x4* p = (const f32x4*)(SS + (size_t)row * 16);
;     const f32x4 a = p[0], b = p[1], c = p[2], d = p[3];
;     const float s = ((a[0] + a[1]) + (a[2] + a[3])) + ((b[0] + b[1]) + (b[2] + b[3])) + ((c[0] + c[1]) + (c[2] + c[3])) + ((d[0] + d[1]) + (d[2] + d[3]));
;     return 1.0f / sqrtf(s * (1.0f / 1024.0f) + 1e-6f);
; }
; DI void fill_rowscales(const pg8::StaticOrder& S, const float* SS, LAS float* rs, int bycol) {
;     pg8::Unit u;
;     for (int ui = 0; ui < RS_SLOTS && S.next(ui, u); ++ui) {
;         const int t = threadIdx.x;
;         if (t < 256) rs[ui * 256 + t] = pg8::rowscale(SS, (bycol ? u.pn : u.pm) * 256 + t);
;     }
	v_add_f32_e32 v9, v48, v49
	v_add_f32_e32 v13, v50, v51
	v_add_f32_e32 v9, v9, v13
	v_add_f32_e32 v10, v52, v53
	v_add_f32_e32 v13, v54, v55
	v_add_f32_e32 v10, v10, v13
	v_add_f32_e32 v11, v56, v57
	v_add_f32_e32 v13, v58, v59
	v_add_f32_e32 v11, v11, v13
	v_add_f32_e32 v12, v60, v61
	v_add_f32_e32 v13, v62, v63
	v_add_f32_e32 v12, v12, v13
	v_add_f32_e32 v9, v9, v10
	v_add_f32_e32 v9, v9, v11
	v_add_f32_e32 v9, v9, v12
	v_fmamk_f32 v9, v9, 0x3a800000, v3
	v_mul_f32_e32 v10, 0x4f800000, v9
	v_cmp_gt_f32_e32 vcc, s16, v9
	s_nop 1
	v_cndmask_b32_e32 v9, v9, v10, vcc
	v_sqrt_f32_e32 v10, v9
	s_nop 0
	v_add_u32_e32 v11, -1, v10
	v_add_u32_e32 v12, 1, v10
	v_fma_f32 v13, -v11, v10, v9
	v_fma_f32 v14, -v12, v10, v9
	v_cmp_ge_f32_e64 s[4:5], 0, v13
	s_nop 1
	v_cndmask_b32_e64 v10, v10, v11, s[4:5]
	v_cmp_lt_f32_e64 s[4:5], 0, v14
	s_nop 1
	v_cndmask_b32_e64 v10, v10, v12, s[4:5]
	v_mul_f32_e32 v11, 0x37800000, v10
	v_cndmask_b32_e32 v10, v10, v11, vcc
	v_cmp_class_f32_e32 vcc, v9, v4
	s_nop 1
	v_cndmask_b32_e32 v9, v10, v9, vcc
	v_div_scale_f32 v10, s[4:5], v9, v9, 1.0
	v_rcp_f32_e32 v11, v10
	v_div_scale_f32 v12, vcc, 1.0, v9, 1.0
	v_fma_f32 v13, -v10, v11, 1.0
	v_fmac_f32_e32 v11, v13, v11
	v_mul_f32_e32 v13, v12, v11
	v_fma_f32 v14, -v10, v13, v12
	v_fmac_f32_e32 v13, v14, v11
	v_fma_f32 v10, -v10, v13, v12
	v_div_fmas_f32 v10, v10, v11, v13
	v_div_fixup_f32 v9, v10, v9, 1.0
	ds_write_b32 v2, v9 offset:2048
	s_waitcnt vmcnt(12)
	v_add_f32_e32 v9, v64, v65
	v_add_f32_e32 v13, v66, v67
	v_add_f32_e32 v9, v9, v13
	v_add_f32_e32 v10, v68, v69
	v_add_f32_e32 v13, v70, v71
	v_add_f32_e32 v10, v10, v13
	v_add_f32_e32 v11, v72, v73
	v_add_f32_e32 v13, v74, v75
	v_add_f32_e32 v11, v11, v13
	v_add_f32_e32 v12, v76, v77
	v_add_f32_e32 v13, v78, v79
	v_add_f32_e32 v12, v12, v13
	v_add_f32_e32 v9, v9, v10
	v_add_f32_e32 v9, v9, v11
	v_add_f32_e32 v9, v9, v12
	v_fmamk_f32 v9, v9, 0x3a800000, v3
	v_mul_f32_e32 v10, 0x4f800000, v9
	v_cmp_gt_f32_e32 vcc, s16, v9
	s_nop 1
	v_cndmask_b32_e32 v9, v9, v10, vcc
	v_sqrt_f32_e32 v10, v9
	s_nop 0
	v_add_u32_e32 v11, -1, v10
	v_add_u32_e32 v12, 1, v10
	v_fma_f32 v13, -v11, v10, v9
	v_fma_f32 v14, -v12, v10, v9
	v_cmp_ge_f32_e64 s[4:5], 0, v13
	s_nop 1
	v_cndmask_b32_e64 v10, v10, v11, s[4:5]
	v_cmp_lt_f32_e64 s[4:5], 0, v14
	s_nop 1
	v_cndmask_b32_e64 v10, v10, v12, s[4:5]
	v_mul_f32_e32 v11, 0x37800000, v10
	v_cndmask_b32_e32 v10, v10, v11, vcc
	v_cmp_class_f32_e32 vcc, v9, v4
	s_nop 1
	v_cndmask_b32_e32 v9, v10, v9, vcc
	v_div_scale_f32 v10, s[4:5], v9, v9, 1.0
	v_rcp_f32_e32 v11, v10
	v_div_scale_f32 v12, vcc, 1.0, v9, 1.0
	v_fma_f32 v13, -v10, v11, 1.0
	v_fmac_f32_e32 v11, v13, v11
	v_mul_f32_e32 v13, v12, v11
	v_fma_f32 v14, -v10, v13, v12
	v_fmac_f32_e32 v13, v14, v11
	v_fma_f32 v10, -v10, v13, v12
	v_div_fmas_f32 v10, v10, v11, v13
	v_div_fixup_f32 v9, v10, v9, 1.0
	ds_write_b32 v2, v9 offset:4096
	s_waitcnt vmcnt(8)
	v_add_f32_e32 v9, v80, v81
	v_add_f32_e32 v13, v82, v83
	v_add_f32_e32 v9, v9, v13
	v_add_f32_e32 v10, v84, v85
	v_add_f32_e32 v13, v86, v87
	v_add_f32_e32 v10, v10, v13
	v_add_f32_e32 v11, v88, v89
	v_add_f32_e32 v13, v90, v91
	v_add_f32_e32 v11, v11, v13
	v_add_f32_e32 v12, v92, v93
	v_add_f32_e32 v13, v94, v95
	v_add_f32_e32 v12, v12, v13
	v_add_f32_e32 v9, v9, v10
	v_add_f32_e32 v9, v9, v11
	v_add_f32_e32 v9, v9, v12
	v_fmamk_f32 v9, v9, 0x3a800000, v3
	v_mul_f32_e32 v10, 0x4f800000, v9
	v_cmp_gt_f32_e32 vcc, s16, v9
	s_nop 1
	v_cndmask_b32_e32 v9, v9, v10, vcc
	v_sqrt_f32_e32 v10, v9
	s_nop 0
	v_add_u32_e32 v11, -1, v10
	v_add_u32_e32 v12, 1, v10
	v_fma_f32 v13, -v11, v10, v9
	v_fma_f32 v14, -v12, v10, v9
	v_cmp_ge_f32_e64 s[4:5], 0, v13
	s_nop 1
	v_cndmask_b32_e64 v10, v10, v11, s[4:5]
	v_cmp_lt_f32_e64 s[4:5], 0, v14
	s_nop 1
	v_cndmask_b32_e64 v10, v10, v12, s[4:5]
	v_mul_f32_e32 v11, 0x37800000, v10
	v_cndmask_b32_e32 v10, v10, v11, vcc
	v_cmp_class_f32_e32 vcc, v9, v4
	s_nop 1
	v_cndmask_b32_e32 v9, v10, v9, vcc
	v_div_scale_f32 v10, s[4:5], v9, v9, 1.0
	v_rcp_f32_e32 v11, v10
	v_div_scale_f32 v12, vcc, 1.0, v9, 1.0
	v_fma_f32 v13, -v10, v11, 1.0
	v_fmac_f32_e32 v11, v13, v11
	v_mul_f32_e32 v13, v12, v11
	v_fma_f32 v14, -v10, v13, v12
	v_fmac_f32_e32 v13, v14, v11
	v_fma_f32 v10, -v10, v13, v12
	v_div_fmas_f32 v10, v10, v11, v13
	v_div_fixup_f32 v9, v10, v9, 1.0
	ds_write_b32 v2, v9 offset:6144
	s_waitcnt vmcnt(4)
; #define LAS __attribute__((address_space(3)))
; __device__ __forceinline__ float rowscale(const float* SS, int row) {
;     const f32x4* p = (const f32x4*)(SS + (size_t)row * 16);
;     const f32x4 a = p[0], b = p[1], c = p[2], d = p[3];
;     const float s = ((a[0] + a[1]) + (a[2] + a[3])) + ((b[0] + b[1]) + (b[2] + b[3])) + ((c[0] + c[1]) + (c[2] + c[3])) + ((d[0] + d[1]) + (d[2] + d[3]));
;     return 1.0f / sqrtf(s * (1.0f / 1024.0f) + 1e-6f);
; }
; DI void fill_rowscales(const pg8::StaticOrder& S, const float* SS, LAS float* rs, int bycol) {
;     pg8::Unit u;
;     for (int ui = 0; ui < RS_SLOTS && S.next(ui, u); ++ui) {
;         const int t = threadIdx.x;
;         if (t < 256) rs[ui * 256 + t] = pg8::rowscale(SS, (bycol ? u.pn : u.pm) * 256 + t);
;     }
	v_add_f32_e32 v9, v96, v97
	v_add_f32_e32 v13, v98, v99
	v_add_f32_e32 v9, v9, v13
	v_add_f32_e32 v10, v100, v101
	v_add_f32_e32 v13, v102, v103
	v_add_f32_e32 v10, v10, v13
	v_add_f32_e32 v11, v104, v105
	v_add_f32_e32 v13, v106, v107
	v_add_f32_e32 v11, v11, v13
	v_add_f32_e32 v12, v108, v109
	v_add_f32_e32 v13, v110, v111
	v_add_f32_e32 v12, v12, v13
	v_add_f32_e32 v9, v9, v10
	v_add_f32_e32 v9, v9, v11
	v_add_f32_e32 v9, v9, v12
	v_fmamk_f32 v9, v9, 0x3a800000, v3
	v_mul_f32_e32 v10, 0x4f800000, v9
	v_cmp_gt_f32_e32 vcc, s16, v9
	s_nop 1
	v_cndmask_b32_e32 v9, v9, v10, vcc
	v_sqrt_f32_e32 v10, v9
	s_nop 0
	v_add_u32_e32 v11, -1, v10
	v_add_u32_e32 v12, 1, v10
	v_fma_f32 v13, -v11, v10, v9
	v_fma_f32 v14, -v12, v10, v9
	v_cmp_ge_f32_e64 s[4:5], 0, v13
	s_nop 1
	v_cndmask_b32_e64 v10, v10, v11, s[4:5]
	v_cmp_lt_f32_e64 s[4:5], 0, v14
	s_nop 1
	v_cndmask_b32_e64 v10, v10, v12, s[4:5]
	v_mul_f32_e32 v11, 0x37800000, v10
	v_cndmask_b32_e32 v10, v10, v11, vcc
	v_cmp_class_f32_e32 vcc, v9, v4
	s_nop 1
	v_cndmask_b32_e32 v9, v10, v9, vcc
	v_div_scale_f32 v10, s[4:5], v9, v9, 1.0
	v_rcp_f32_e32 v11, v10
	v_div_scale_f32 v12, vcc, 1.0, v9, 1.0
	v_fma_f32 v13, -v10, v11, 1.0
	v_fmac_f32_e32 v11, v13, v11
	v_mul_f32_e32 v13, v12, v11
	v_fma_f32 v14, -v10, v13, v12
	v_fmac_f32_e32 v13, v14, v11
	v_fma_f32 v10, -v10, v13, v12
	v_div_fmas_f32 v10, v10, v11, v13
	v_div_fixup_f32 v9, v10, v9, 1.0
	ds_write_b32 v2, v9 offset:8192
	s_waitcnt vmcnt(0)
	v_add_f32_e32 v9, v112, v113
	v_add_f32_e32 v13, v114, v115
	v_add_f32_e32 v9, v9, v13
	v_add_f32_e32 v10, v116, v117
	v_add_f32_e32 v13, v118, v119
	v_add_f32_e32 v10, v10, v13
	v_add_f32_e32 v11, v120, v121
	v_add_f32_e32 v13, v122, v123
	v_add_f32_e32 v11, v11, v13
	v_add_f32_e32 v12, v124, v125
	v_add_f32_e32 v13, v126, v127
	v_add_f32_e32 v12, v12, v13
	v_add_f32_e32 v9, v9, v10
	v_add_f32_e32 v9, v9, v11
	v_add_f32_e32 v9, v9, v12
	v_fmamk_f32 v9, v9, 0x3a800000, v3
	v_mul_f32_e32 v10, 0x4f800000, v9
	v_cmp_gt_f32_e32 vcc, s16, v9
	s_nop 1
	v_cndmask_b32_e32 v9, v9, v10, vcc
	v_sqrt_f32_e32 v10, v9
	s_nop 0
	v_add_u32_e32 v11, -1, v10
	v_add_u32_e32 v12, 1, v10
	v_fma_f32 v13, -v11, v10, v9
	v_fma_f32 v14, -v12, v10, v9
	v_cmp_ge_f32_e64 s[4:5], 0, v13
	s_nop 1
	v_cndmask_b32_e64 v10, v10, v11, s[4:5]
	v_cmp_lt_f32_e64 s[4:5], 0, v14
	s_nop 1
	v_cndmask_b32_e64 v10, v10, v12, s[4:5]
	v_mul_f32_e32 v11, 0x37800000, v10
	v_cndmask_b32_e32 v10, v10, v11, vcc
	v_cmp_class_f32_e32 vcc, v9, v4
	s_nop 1
	v_cndmask_b32_e32 v9, v10, v9, vcc
	v_div_scale_f32 v10, s[4:5], v9, v9, 1.0
	v_rcp_f32_e32 v11, v10
	v_div_scale_f32 v12, vcc, 1.0, v9, 1.0
	v_fma_f32 v13, -v10, v11, 1.0
	v_fmac_f32_e32 v11, v13, v11
	v_mul_f32_e32 v13, v12, v11
	v_fma_f32 v14, -v10, v13, v12
	v_fmac_f32_e32 v13, v14, v11
	v_fma_f32 v10, -v10, v13, v12
	v_div_fmas_f32 v10, v10, v11, v13
	v_div_fixup_f32 v9, v10, v9, 1.0
	ds_write_b32 v2, v9 offset:10240

; #define LAS __attribute__((address_space(3)))
;     __host__ __device__ bool next(int i, Unit& u) const {
;         const long L = (long)i * G + c; if (L >= nwg) return false;
;         int wgid = (int)L; { const int q = nwg / NXCD, r = nwg % NXCD, xcd = wgid % NXCD, off = wgid / NXCD; wgid = (xcd < r ? xcd * (q + 1) : r * (q + 1) + (xcd - r) * q) + off; }
;         const int nig = WGM * nN, gid = wgid / nig, fm = gid * WGM, gsz = (nM - fm) < WGM ? (nM - fm) : WGM;
;         u.pm = fm + ((wgid % nig) % gsz); u.pn = (wgid % nig) / gsz; return true;
;     }
; __device__ __forceinline__ u32x4 pk8(const f32x4 a, const f32x4 b) { u32x4 w; w.x = pk2(a[0], a[1]); w.y = pk2(a[2], a[3]); w.z = pk2(b[0], b[1]); w.w = pk2(b[2], b[3]); return w; }
; __device__ __forceinline__ float rowscale(const float* SS, int row) {
;     const f32x4* p = (const f32x4*)(SS + (size_t)row * 16);
;     const f32x4 a = p[0], b = p[1], c = p[2], d = p[3];
;     const float s = ((a[0] + a[1]) + (a[2] + a[3])) + ((b[0] + b[1]) + (b[2] + b[3])) + ((c[0] + c[1]) + (c[2] + c[3])) + ((d[0] + d[1]) + (d[2] + d[3]));
;     return 1.0f / sqrtf(s * (1.0f / 1024.0f) + 1e-6f);
; }
; DI void fill_rowscales(const pg8::StaticOrder& S, const float* SS, LAS float* rs, int bycol) {
;     pg8::Unit u;
;     for (int ui = 0; ui < RS_SLOTS && S.next(ui, u); ++ui) {
;         const int t = threadIdx.x;
;         if (t < 256) rs[ui * 256 + t] = pg8::rowscale(SS, (bycol ? u.pn : u.pm) * 256 + t);
;     }
.LBB0_1034:
	s_add_u32 s6, s90, 0x5900000
	s_waitcnt vmcnt(0)
	v_lshlrev_b32_e32 v8, 2, v254
	s_addc_u32 s7, s91, 0
	s_ashr_i32 s3, s2, 31
	s_movk_i32 s0, 0x100
	v_add_u32_e32 v0, 0, v8
	s_ashr_i32 s30, s94, 31
	s_mov_b32 s31, s94
	v_cmp_gt_u32_e64 s[0:1], s0, v254
	v_add_u32_e32 v2, 0x20000, v0
	s_movk_i32 s14, 0xd000
	s_waitcnt lgkmcnt(0)
	v_mov_b64_e32 v[0:1], 0xaff
	s_movk_i32 s15, 0x161
	v_mov_b32_e32 v3, 0x358637bd
	s_mov_b32 s16, 0xf800000
	v_mov_b32_e32 v4, 0x260
	s_mov_b64 s[8:9], s[2:3]
	v_readfirstlane_b32 s12, v254
	v_and_b32_e32 v5, 0xff, v254
	s_nop 3
	s_lshr_b32 s12, s12, 8
	s_mul_i32 s13, s12, s31
	s_add_i32 s8, s2, s13
	s_lshl_b32 s9, s31, 1
	s_cmp_lt_u32 s8, 0xb00
	s_cselect_b32 s4, s8, s2
	s_and_b32 s5, s4, 7
	s_lshr_b32 s4, s4, 3
	s_mul_i32 s5, s5, 0x160
	s_add_i32 s4, s4, s5
	s_mul_hi_u32 s5, s4, 0x1745d18
	s_mul_i32 s13, s5, 0xb0
	s_sub_i32 s13, s4, s13
	s_and_b32 s13, s13, 7
	s_lshl_b32 s5, s5, 3
	s_add_i32 s5, s5, s13
	v_lshl_or_b32 v26, s5, 8, v5
	v_lshlrev_b32_e32 v26, 6, v26
	s_add_i32 s8, s8, s9
	global_load_dwordx4 v[32:35], v26, s[6:7]
	global_load_dwordx4 v[36:39], v26, s[6:7] offset:16
	global_load_dwordx4 v[40:43], v26, s[6:7] offset:32
	global_load_dwordx4 v[44:47], v26, s[6:7] offset:48
	s_cmp_lt_u32 s8, 0xb00
	s_cselect_b32 s4, s8, s2
	s_and_b32 s5, s4, 7
	s_lshr_b32 s4, s4, 3
	s_mul_i32 s5, s5, 0x160
	s_add_i32 s4, s4, s5
	s_mul_hi_u32 s5, s4, 0x1745d18
	s_mul_i32 s13, s5, 0xb0
	s_sub_i32 s13, s4, s13
	s_and_b32 s13, s13, 7
	s_lshl_b32 s5, s5, 3
	s_add_i32 s5, s5, s13
	v_lshl_or_b32 v27, s5, 8, v5
	v_lshlrev_b32_e32 v27, 6, v27
	s_add_i32 s8, s8, s9
	global_load_dwordx4 v[48:51], v27, s[6:7]
	global_load_dwordx4 v[52:55], v27, s[6:7] offset:16
	global_load_dwordx4 v[56:59], v27, s[6:7] offset:32
	global_load_dwordx4 v[60:63], v27, s[6:7] offset:48
	s_cmp_lt_u32 s8, 0xb00
	s_cselect_b32 s4, s8, s2
	s_and_b32 s5, s4, 7
	s_lshr_b32 s4, s4, 3
	s_mul_i32 s5, s5, 0x160
	s_add_i32 s4, s4, s5
	s_mul_hi_u32 s5, s4, 0x1745d18
	s_mul_i32 s13, s5, 0xb0
	s_sub_i32 s13, s4, s13
	s_and_b32 s13, s13, 7
	s_lshl_b32 s5, s5, 3
	s_add_i32 s5, s5, s13
	v_lshl_or_b32 v28, s5, 8, v5
	v_lshlrev_b32_e32 v28, 6, v28
	s_add_i32 s8, s8, s9
	global_load_dwordx4 v[64:67], v28, s[6:7]
	global_load_dwordx4 v[68:71], v28, s[6:7] offset:16
	global_load_dwordx4 v[72:75], v28, s[6:7] offset:32
	global_load_dwordx4 v[76:79], v28, s[6:7] offset:48
	s_cmp_lt_u32 s8, 0xb00
	s_cselect_b32 s4, s8, s2
	s_and_b32 s5, s4, 7
	s_lshr_b32 s4, s4, 3
	s_mul_i32 s5, s5, 0x160
	s_add_i32 s4, s4, s5
	s_mul_hi_u32 s5, s4, 0x1745d18
	s_mul_i32 s13, s5, 0xb0
	s_sub_i32 s13, s4, s13
	s_and_b32 s13, s13, 7
	s_lshl_b32 s5, s5, 3
	s_add_i32 s5, s5, s13
	v_lshl_or_b32 v29, s5, 8, v5
	v_lshlrev_b32_e32 v29, 6, v29
	s_add_i32 s8, s8, s9
	global_load_dwordx4 v[80:83], v29, s[6:7]
	global_load_dwordx4 v[84:87], v29, s[6:7] offset:16
	global_load_dwordx4 v[88:91], v29, s[6:7] offset:32
	global_load_dwordx4 v[92:95], v29, s[6:7] offset:48
	s_cmp_lt_u32 s8, 0xb00
	s_cselect_b32 s4, s8, s2
	s_and_b32 s5, s4, 7
	s_lshr_b32 s4, s4, 3
	s_mul_i32 s5, s5, 0x160
	s_add_i32 s4, s4, s5
	s_mul_hi_u32 s5, s4, 0x1745d18
	s_mul_i32 s13, s5, 0xb0
	s_sub_i32 s13, s4, s13
	s_and_b32 s13, s13, 7
	s_lshl_b32 s5, s5, 3
	s_add_i32 s5, s5, s13
	v_lshl_or_b32 v30, s5, 8, v5
	v_lshlrev_b32_e32 v30, 6, v30
	s_add_i32 s8, s8, s9
	global_load_dwordx4 v[96:99], v30, s[6:7]
	global_load_dwordx4 v[100:103], v30, s[6:7] offset:16
	global_load_dwordx4 v[104:107], v30, s[6:7] offset:32
	global_load_dwordx4 v[108:111], v30, s[6:7] offset:48
	s_cmp_lt_u32 s8, 0xb00
	s_cselect_b32 s4, s8, s2
	s_and_b32 s5, s4, 7
	s_lshr_b32 s4, s4, 3
	s_mul_i32 s5, s5, 0x160
	s_add_i32 s4, s4, s5
	s_mul_hi_u32 s5, s4, 0x1745d18
	s_mul_i32 s13, s5, 0xb0
	s_sub_i32 s13, s4, s13
	s_and_b32 s13, s13, 7
	s_lshl_b32 s5, s5, 3
	s_add_i32 s5, s5, s13
	v_lshl_or_b32 v31, s5, 8, v5
	v_lshlrev_b32_e32 v31, 6, v31
	s_add_i32 s8, s8, s9
	global_load_dwordx4 v[112:115], v31, s[6:7]
	global_load_dwordx4 v[116:119], v31, s[6:7] offset:16
	global_load_dwordx4 v[120:123], v31, s[6:7] offset:32
	global_load_dwordx4 v[124:127], v31, s[6:7] offset:48
	s_waitcnt vmcnt(20)
	v_add_f32_e32 v9, v32, v33
	v_add_f32_e32 v13, v34, v35
	v_add_f32_e32 v9, v9, v13
	v_add_f32_e32 v10, v36, v37
	v_add_f32_e32 v13, v38, v39
	v_add_f32_e32 v10, v10, v13
	v_add_f32_e32 v11, v40, v41
	v_add_f32_e32 v13, v42, v43
	v_add_f32_e32 v11, v11, v13
	v_add_f32_e32 v12, v44, v45
	v_add_f32_e32 v13, v46, v47
	v_add_f32_e32 v12, v12, v13
	v_add_f32_e32 v9, v9, v10
	v_add_f32_e32 v9, v9, v11
	v_add_f32_e32 v9, v9, v12
	v_fmamk_f32 v9, v9, 0x3a800000, v3
	v_mul_f32_e32 v10, 0x4f800000, v9
	v_cmp_gt_f32_e32 vcc, s16, v9
	s_nop 1
	v_cndmask_b32_e32 v9, v9, v10, vcc
	v_sqrt_f32_e32 v10, v9
	s_nop 0
	v_add_u32_e32 v11, -1, v10
	v_add_u32_e32 v12, 1, v10
	v_fma_f32 v13, -v11, v10, v9
	v_fma_f32 v14, -v12, v10, v9
	v_cmp_ge_f32_e64 s[4:5], 0, v13
	s_nop 1
	v_cndmask_b32_e64 v10, v10, v11, s[4:5]
	v_cmp_lt_f32_e64 s[4:5], 0, v14
	s_nop 1
	v_cndmask_b32_e64 v10, v10, v12, s[4:5]
	v_mul_f32_e32 v11, 0x37800000, v10
	v_cndmask_b32_e32 v10, v10, v11, vcc
	v_cmp_class_f32_e32 vcc, v9, v4
	s_nop 1
	v_cndmask_b32_e32 v9, v10, v9, vcc
	v_div_scale_f32 v10, s[4:5], v9, v9, 1.0
	v_rcp_f32_e32 v11, v10
	v_div_scale_f32 v12, vcc, 1.0, v9, 1.0
	v_fma_f32 v13, -v10, v11, 1.0
	v_fmac_f32_e32 v11, v13, v11
	v_mul_f32_e32 v13, v12, v11
	v_fma_f32 v14, -v10, v13, v12
	v_fmac_f32_e32 v13, v14, v11
	v_fma_f32 v10, -v10, v13, v12
	v_div_fmas_f32 v10, v10, v11, v13
	v_div_fixup_f32 v9, v10, v9, 1.0
	ds_write_b32 v2, v9
	s_waitcnt vmcnt(16)
; #define LAS __attribute__((address_space(3)))
; __device__ __forceinline__ float rowscale(const float* SS, int row) {
;     const f32x4* p = (const f32x4*)(SS + (size_t)row * 16);
;     const f32x4 a = p[0], b = p[1], c = p[2], d = p[3];
;     const float s = ((a[0] + a[1]) + (a[2] + a[3])) + ((b[0] + b[1]) + (b[2] + b[3])) + ((c[0] + c[1]) + (c[2] + c[3])) + ((d[0] + d[1]) + (d[2] + d[3]));
;     return 1.0f / sqrtf(s * (1.0f / 1024.0f) + 1e-6f);
; }
; DI void fill_rowscales(const pg8::StaticOrder& S, const float* SS, LAS float* rs, int bycol) {
;     pg8::Unit u;
;     for (int ui = 0; ui < RS_SLOTS && S.next(ui, u); ++ui) {
;         const int t = threadIdx.x;
;         if (t < 256) rs[ui * 256 + t] = pg8::rowscale(SS, (bycol ? u.pn : u.pm) * 256 + t);
;     }
	v_add_f32_e32 v9, v48, v49
	v_add_f32_e32 v13, v50, v51
	v_add_f32_e32 v9, v9, v13
	v_add_f32_e32 v10, v52, v53
	v_add_f32_e32 v13, v54, v55
	v_add_f32_e32 v10, v10, v13
	v_add_f32_e32 v11, v56, v57
	v_add_f32_e32 v13, v58, v59
	v_add_f32_e32 v11, v11, v13
	v_add_f32_e32 v12, v60, v61
	v_add_f32_e32 v13, v62, v63
	v_add_f32_e32 v12, v12, v13
	v_add_f32_e32 v9, v9, v10
	v_add_f32_e32 v9, v9, v11
	v_add_f32_e32 v9, v9, v12
	v_fmamk_f32 v9, v9, 0x3a800000, v3
	v_mul_f32_e32 v10, 0x4f800000, v9
	v_cmp_gt_f32_e32 vcc, s16, v9
	s_nop 1
	v_cndmask_b32_e32 v9, v9, v10, vcc
	v_sqrt_f32_e32 v10, v9
	s_nop 0
	v_add_u32_e32 v11, -1, v10
	v_add_u32_e32 v12, 1, v10
	v_fma_f32 v13, -v11, v10, v9
	v_fma_f32 v14, -v12, v10, v9
	v_cmp_ge_f32_e64 s[4:5], 0, v13
	s_nop 1
	v_cndmask_b32_e64 v10, v10, v11, s[4:5]
	v_cmp_lt_f32_e64 s[4:5], 0, v14
	s_nop 1
	v_cndmask_b32_e64 v10, v10, v12, s[4:5]
	v_mul_f32_e32 v11, 0x37800000, v10
	v_cndmask_b32_e32 v10, v10, v11, vcc
	v_cmp_class_f32_e32 vcc, v9, v4
	s_nop 1
	v_cndmask_b32_e32 v9, v10, v9, vcc
	v_div_scale_f32 v10, s[4:5], v9, v9, 1.0
	v_rcp_f32_e32 v11, v10
	v_div_scale_f32 v12, vcc, 1.0, v9, 1.0
	v_fma_f32 v13, -v10, v11, 1.0
	v_fmac_f32_e32 v11, v13, v11
	v_mul_f32_e32 v13, v12, v11
	v_fma_f32 v14, -v10, v13, v12
	v_fmac_f32_e32 v13, v14, v11
	v_fma_f32 v10, -v10, v13, v12
	v_div_fmas_f32 v10, v10, v11, v13
	v_div_fixup_f32 v9, v10, v9, 1.0
	ds_write_b32 v2, v9 offset:2048
	s_waitcnt vmcnt(12)
	v_add_f32_e32 v9, v64, v65
	v_add_f32_e32 v13, v66, v67
	v_add_f32_e32 v9, v9, v13
	v_add_f32_e32 v10, v68, v69
	v_add_f32_e32 v13, v70, v71
	v_add_f32_e32 v10, v10, v13
	v_add_f32_e32 v11, v72, v73
	v_add_f32_e32 v13, v74, v75
	v_add_f32_e32 v11, v11, v13
	v_add_f32_e32 v12, v76, v77
	v_add_f32_e32 v13, v78, v79
	v_add_f32_e32 v12, v12, v13
	v_add_f32_e32 v9, v9, v10
	v_add_f32_e32 v9, v9, v11
	v_add_f32_e32 v9, v9, v12
	v_fmamk_f32 v9, v9, 0x3a800000, v3
	v_mul_f32_e32 v10, 0x4f800000, v9
	v_cmp_gt_f32_e32 vcc, s16, v9
	s_nop 1
	v_cndmask_b32_e32 v9, v9, v10, vcc
	v_sqrt_f32_e32 v10, v9
	s_nop 0
	v_add_u32_e32 v11, -1, v10
	v_add_u32_e32 v12, 1, v10
	v_fma_f32 v13, -v11, v10, v9
	v_fma_f32 v14, -v12, v10, v9
	v_cmp_ge_f32_e64 s[4:5], 0, v13
	s_nop 1
	v_cndmask_b32_e64 v10, v10, v11, s[4:5]
	v_cmp_lt_f32_e64 s[4:5], 0, v14
	s_nop 1
	v_cndmask_b32_e64 v10, v10, v12, s[4:5]
	v_mul_f32_e32 v11, 0x37800000, v10
	v_cndmask_b32_e32 v10, v10, v11, vcc
	v_cmp_class_f32_e32 vcc, v9, v4
	s_nop 1
	v_cndmask_b32_e32 v9, v10, v9, vcc
	v_div_scale_f32 v10, s[4:5], v9, v9, 1.0
	v_rcp_f32_e32 v11, v10
	v_div_scale_f32 v12, vcc, 1.0, v9, 1.0
	v_fma_f32 v13, -v10, v11, 1.0
	v_fmac_f32_e32 v11, v13, v11
	v_mul_f32_e32 v13, v12, v11
	v_fma_f32 v14, -v10, v13, v12
	v_fmac_f32_e32 v13, v14, v11
	v_fma_f32 v10, -v10, v13, v12
	v_div_fmas_f32 v10, v10, v11, v13
	v_div_fixup_f32 v9, v10, v9, 1.0
	ds_write_b32 v2, v9 offset:4096
	s_waitcnt vmcnt(8)
	v_add_f32_e32 v9, v80, v81
	v_add_f32_e32 v13, v82, v83
	v_add_f32_e32 v9, v9, v13
	v_add_f32_e32 v10, v84, v85
	v_add_f32_e32 v13, v86, v87
	v_add_f32_e32 v10, v10, v13
	v_add_f32_e32 v11, v88, v89
	v_add_f32_e32 v13, v90, v91
	v_add_f32_e32 v11, v11, v13
	v_add_f32_e32 v12, v92, v93
	v_add_f32_e32 v13, v94, v95
	v_add_f32_e32 v12, v12, v13
	v_add_f32_e32 v9, v9, v10
	v_add_f32_e32 v9, v9, v11
	v_add_f32_e32 v9, v9, v12
	v_fmamk_f32 v9, v9, 0x3a800000, v3
	v_mul_f32_e32 v10, 0x4f800000, v9
	v_cmp_gt_f32_e32 vcc, s16, v9
	s_nop 1
	v_cndmask_b32_e32 v9, v9, v10, vcc
	v_sqrt_f32_e32 v10, v9
	s_nop 0
	v_add_u32_e32 v11, -1, v10
	v_add_u32_e32 v12, 1, v10
	v_fma_f32 v13, -v11, v10, v9
	v_fma_f32 v14, -v12, v10, v9
	v_cmp_ge_f32_e64 s[4:5], 0, v13
	s_nop 1
	v_cndmask_b32_e64 v10, v10, v11, s[4:5]
	v_cmp_lt_f32_e64 s[4:5], 0, v14
	s_nop 1
	v_cndmask_b32_e64 v10, v10, v12, s[4:5]
	v_mul_f32_e32 v11, 0x37800000, v10
	v_cndmask_b32_e32 v10, v10, v11, vcc
	v_cmp_class_f32_e32 vcc, v9, v4
	s_nop 1
	v_cndmask_b32_e32 v9, v10, v9, vcc
	v_div_scale_f32 v10, s[4:5], v9, v9, 1.0
	v_rcp_f32_e32 v11, v10
	v_div_scale_f32 v12, vcc, 1.0, v9, 1.0
	v_fma_f32 v13, -v10, v11, 1.0
	v_fmac_f32_e32 v11, v13, v11
	v_mul_f32_e32 v13, v12, v11
	v_fma_f32 v14, -v10, v13, v12
	v_fmac_f32_e32 v13, v14, v11
	v_fma_f32 v10, -v10, v13, v12
	v_div_fmas_f32 v10, v10, v11, v13
	v_div_fixup_f32 v9, v10, v9, 1.0
	ds_write_b32 v2, v9 offset:6144
	s_waitcnt vmcnt(4)
; #define LAS __attribute__((address_space(3)))
; __device__ __forceinline__ float rowscale(const float* SS, int row) {
;     const f32x4* p = (const f32x4*)(SS + (size_t)row * 16);
;     const f32x4 a = p[0], b = p[1], c = p[2], d = p[3];
;     const float s = ((a[0] + a[1]) + (a[2] + a[3])) + ((b[0] + b[1]) + (b[2] + b[3])) + ((c[0] + c[1]) + (c[2] + c[3])) + ((d[0] + d[1]) + (d[2] + d[3]));
;     return 1.0f / sqrtf(s * (1.0f / 1024.0f) + 1e-6f);
; }
; DI void fill_rowscales(const pg8::StaticOrder& S, const float* SS, LAS float* rs, int bycol) {
;     pg8::Unit u;
;     for (int ui = 0; ui < RS_SLOTS && S.next(ui, u); ++ui) {
;         const int t = threadIdx.x;
;         if (t < 256) rs[ui * 256 + t] = pg8::rowscale(SS, (bycol ? u.pn : u.pm) * 256 + t);
;     }
	v_add_f32_e32 v9, v96, v97
	v_add_f32_e32 v13, v98, v99
	v_add_f32_e32 v9, v9, v13
	v_add_f32_e32 v10, v100, v101
	v_add_f32_e32 v13, v102, v103
	v_add_f32_e32 v10, v10, v13
	v_add_f32_e32 v11, v104, v105
	v_add_f32_e32 v13, v106, v107
	v_add_f32_e32 v11, v11, v13
	v_add_f32_e32 v12, v108, v109
	v_add_f32_e32 v13, v110, v111
	v_add_f32_e32 v12, v12, v13
	v_add_f32_e32 v9, v9, v10
	v_add_f32_e32 v9, v9, v11
	v_add_f32_e32 v9, v9, v12
	v_fmamk_f32 v9, v9, 0x3a800000, v3
	v_mul_f32_e32 v10, 0x4f800000, v9
	v_cmp_gt_f32_e32 vcc, s16, v9
	s_nop 1
	v_cndmask_b32_e32 v9, v9, v10, vcc
	v_sqrt_f32_e32 v10, v9
	s_nop 0
	v_add_u32_e32 v11, -1, v10
	v_add_u32_e32 v12, 1, v10
	v_fma_f32 v13, -v11, v10, v9
	v_fma_f32 v14, -v12, v10, v9
	v_cmp_ge_f32_e64 s[4:5], 0, v13
	s_nop 1
	v_cndmask_b32_e64 v10, v10, v11, s[4:5]
	v_cmp_lt_f32_e64 s[4:5], 0, v14
	s_nop 1
	v_cndmask_b32_e64 v10, v10, v12, s[4:5]
	v_mul_f32_e32 v11, 0x37800000, v10
	v_cndmask_b32_e32 v10, v10, v11, vcc
	v_cmp_class_f32_e32 vcc, v9, v4
	s_nop 1
	v_cndmask_b32_e32 v9, v10, v9, vcc
	v_div_scale_f32 v10, s[4:5], v9, v9, 1.0
	v_rcp_f32_e32 v11, v10
	v_div_scale_f32 v12, vcc, 1.0, v9, 1.0
	v_fma_f32 v13, -v10, v11, 1.0
	v_fmac_f32_e32 v11, v13, v11
	v_mul_f32_e32 v13, v12, v11
	v_fma_f32 v14, -v10, v13, v12
	v_fmac_f32_e32 v13, v14, v11
	v_fma_f32 v10, -v10, v13, v12
	v_div_fmas_f32 v10, v10, v11, v13
	v_div_fixup_f32 v9, v10, v9, 1.0
	ds_write_b32 v2, v9 offset:8192
	s_waitcnt vmcnt(0)
	v_add_f32_e32 v9, v112, v113
	v_add_f32_e32 v13, v114, v115
	v_add_f32_e32 v9, v9, v13
	v_add_f32_e32 v10, v116, v117
	v_add_f32_e32 v13, v118, v119
	v_add_f32_e32 v10, v10, v13
	v_add_f32_e32 v11, v120, v121
	v_add_f32_e32 v13, v122, v123
	v_add_f32_e32 v11, v11, v13
	v_add_f32_e32 v12, v124, v125
	v_add_f32_e32 v13, v126, v127
	v_add_f32_e32 v12, v12, v13
	v_add_f32_e32 v9, v9, v10
	v_add_f32_e32 v9, v9, v11
	v_add_f32_e32 v9, v9, v12
	v_fmamk_f32 v9, v9, 0x3a800000, v3
	v_mul_f32_e32 v10, 0x4f800000, v9
	v_cmp_gt_f32_e32 vcc, s16, v9
	s_nop 1
	v_cndmask_b32_e32 v9, v9, v10, vcc
	v_sqrt_f32_e32 v10, v9
	s_nop 0
	v_add_u32_e32 v11, -1, v10
	v_add_u32_e32 v12, 1, v10
	v_fma_f32 v13, -v11, v10, v9
	v_fma_f32 v14, -v12, v10, v9
	v_cmp_ge_f32_e64 s[4:5], 0, v13
	s_nop 1
	v_cndmask_b32_e64 v10, v10, v11, s[4:5]
	v_cmp_lt_f32_e64 s[4:5], 0, v14
	s_nop 1
	v_cndmask_b32_e64 v10, v10, v12, s[4:5]
	v_mul_f32_e32 v11, 0x37800000, v10
	v_cndmask_b32_e32 v10, v10, v11, vcc
	v_cmp_class_f32_e32 vcc, v9, v4
	s_nop 1
	v_cndmask_b32_e32 v9, v10, v9, vcc
	v_div_scale_f32 v10, s[4:5], v9, v9, 1.0
	v_rcp_f32_e32 v11, v10
	v_div_scale_f32 v12, vcc, 1.0, v9, 1.0
	v_fma_f32 v13, -v10, v11, 1.0
	v_fmac_f32_e32 v11, v13, v11
	v_mul_f32_e32 v13, v12, v11
	v_fma_f32 v14, -v10, v13, v12
	v_fmac_f32_e32 v13, v14, v11
	v_fma_f32 v10, -v10, v13, v12
	v_div_fmas_f32 v10, v10, v11, v13
	v_div_fixup_f32 v9, v10, v9, 1.0
	ds_write_b32 v2, v9 offset:10240

; #define LAS __attribute__((address_space(3)))
;     __host__ __device__ bool next(int i, Unit& u) const {
;         const long L = (long)i * G + c; if (L >= nwg) return false;
;         int wgid = (int)L; { const int q = nwg / NXCD, r = nwg % NXCD, xcd = wgid % NXCD, off = wgid / NXCD; wgid = (xcd < r ? xcd * (q + 1) : r * (q + 1) + (xcd - r) * q) + off; }
;         const int nig = WGM * nN, gid = wgid / nig, fm = gid * WGM, gsz = (nM - fm) < WGM ? (nM - fm) : WGM;
;         u.pm = fm + ((wgid % nig) % gsz); u.pn = (wgid % nig) / gsz; return true;
;     }
; __device__ __forceinline__ u32x4 pk8(const f32x4 a, const f32x4 b) { u32x4 w; w.x = pk2(a[0], a[1]); w.y = pk2(a[2], a[3]); w.z = pk2(b[0], b[1]); w.w = pk2(b[2], b[3]); return w; }
; __device__ __forceinline__ float rowscale(const float* SS, int row) {
;     const f32x4* p = (const f32x4*)(SS + (size_t)row * 16);
;     const f32x4 a = p[0], b = p[1], c = p[2], d = p[3];
;     const float s = ((a[0] + a[1]) + (a[2] + a[3])) + ((b[0] + b[1]) + (b[2] + b[3])) + ((c[0] + c[1]) + (c[2] + c[3])) + ((d[0] + d[1]) + (d[2] + d[3]));
;     return 1.0f / sqrtf(s * (1.0f / 1024.0f) + 1e-6f);
; }
; DI void fill_rowscales(const pg8::StaticOrder& S, const float* SS, LAS float* rs, int bycol) {
;     pg8::Unit u;
;     for (int ui = 0; ui < RS_SLOTS && S.next(ui, u); ++ui) {
;         const int t = threadIdx.x;
;         if (t < 256) rs[ui * 256 + t] = pg8::rowscale(SS, (bycol ? u.pn : u.pm) * 256 + t);
;     }
.LBB0_1204:
	s_add_u32 s8, s90, 0x5900000
	s_waitcnt vmcnt(0)
	v_lshlrev_b32_e32 v8, 2, v254
	s_addc_u32 s9, s91, 0
	s_ashr_i32 s3, s2, 31
	s_movk_i32 s0, 0x100
	v_add_u32_e32 v0, 0, v8
	s_ashr_i32 s30, s94, 31
	s_mov_b32 s31, s94
	v_cmp_gt_u32_e64 s[0:1], s0, v254
	v_add_u32_e32 v2, 0x20000, v0
	s_movk_i32 s14, 0xd000
	s_waitcnt lgkmcnt(0)
	v_mov_b64_e32 v[0:1], 0xaff
	s_movk_i32 s15, 0x161
	v_mov_b32_e32 v3, 0x358637bd
	s_mov_b32 s16, 0xf800000
	v_mov_b32_e32 v4, 0x260
	s_mov_b64 s[10:11], s[2:3]
	v_readfirstlane_b32 s12, v254
	v_and_b32_e32 v5, 0xff, v254
	s_nop 3
	s_lshr_b32 s12, s12, 8
	s_mul_i32 s13, s12, s31
	s_add_i32 s10, s2, s13
	s_lshl_b32 s11, s31, 1
	s_cmp_lt_u32 s10, 0xb00
	s_cselect_b32 s4, s10, s2
	s_and_b32 s5, s4, 7
	s_lshr_b32 s4, s4, 3
	s_mul_i32 s5, s5, 0x160
	s_add_i32 s4, s4, s5
	s_mul_hi_u32 s5, s4, 0x1745d18
	s_mul_i32 s13, s5, 0xb0
	s_sub_i32 s13, s4, s13
	s_and_b32 s13, s13, 7
	s_lshl_b32 s5, s5, 3
	s_add_i32 s5, s5, s13
	v_lshl_or_b32 v26, s5, 8, v5
	v_lshlrev_b32_e32 v26, 6, v26
	s_add_i32 s10, s10, s11
	global_load_dwordx4 v[32:35], v26, s[8:9]
	global_load_dwordx4 v[36:39], v26, s[8:9] offset:16
	global_load_dwordx4 v[40:43], v26, s[8:9] offset:32
	global_load_dwordx4 v[44:47], v26, s[8:9] offset:48
	s_cmp_lt_u32 s10, 0xb00
	s_cselect_b32 s4, s10, s2
	s_and_b32 s5, s4, 7
	s_lshr_b32 s4, s4, 3
	s_mul_i32 s5, s5, 0x160
	s_add_i32 s4, s4, s5
	s_mul_hi_u32 s5, s4, 0x1745d18
	s_mul_i32 s13, s5, 0xb0
	s_sub_i32 s13, s4, s13
	s_and_b32 s13, s13, 7
	s_lshl_b32 s5, s5, 3
	s_add_i32 s5, s5, s13
	v_lshl_or_b32 v27, s5, 8, v5
	v_lshlrev_b32_e32 v27, 6, v27
	s_add_i32 s10, s10, s11
	global_load_dwordx4 v[48:51], v27, s[8:9]
	global_load_dwordx4 v[52:55], v27, s[8:9] offset:16
	global_load_dwordx4 v[56:59], v27, s[8:9] offset:32
	global_load_dwordx4 v[60:63], v27, s[8:9] offset:48
	s_cmp_lt_u32 s10, 0xb00
	s_cselect_b32 s4, s10, s2
	s_and_b32 s5, s4, 7
	s_lshr_b32 s4, s4, 3
	s_mul_i32 s5, s5, 0x160
	s_add_i32 s4, s4, s5
	s_mul_hi_u32 s5, s4, 0x1745d18
	s_mul_i32 s13, s5, 0xb0
	s_sub_i32 s13, s4, s13
	s_and_b32 s13, s13, 7
	s_lshl_b32 s5, s5, 3
	s_add_i32 s5, s5, s13
	v_lshl_or_b32 v28, s5, 8, v5
	v_lshlrev_b32_e32 v28, 6, v28
	s_add_i32 s10, s10, s11
	global_load_dwordx4 v[64:67], v28, s[8:9]
	global_load_dwordx4 v[68:71], v28, s[8:9] offset:16
	global_load_dwordx4 v[72:75], v28, s[8:9] offset:32
	global_load_dwordx4 v[76:79], v28, s[8:9] offset:48
	s_cmp_lt_u32 s10, 0xb00
	s_cselect_b32 s4, s10, s2
	s_and_b32 s5, s4, 7
	s_lshr_b32 s4, s4, 3
	s_mul_i32 s5, s5, 0x160
	s_add_i32 s4, s4, s5
	s_mul_hi_u32 s5, s4, 0x1745d18
	s_mul_i32 s13, s5, 0xb0
	s_sub_i32 s13, s4, s13
	s_and_b32 s13, s13, 7
	s_lshl_b32 s5, s5, 3
	s_add_i32 s5, s5, s13
	v_lshl_or_b32 v29, s5, 8, v5
	v_lshlrev_b32_e32 v29, 6, v29
	s_add_i32 s10, s10, s11
	global_load_dwordx4 v[80:83], v29, s[8:9]
	global_load_dwordx4 v[84:87], v29, s[8:9] offset:16
	global_load_dwordx4 v[88:91], v29, s[8:9] offset:32
	global_load_dwordx4 v[92:95], v29, s[8:9] offset:48
	s_cmp_lt_u32 s10, 0xb00
	s_cselect_b32 s4, s10, s2
	s_and_b32 s5, s4, 7
	s_lshr_b32 s4, s4, 3
	s_mul_i32 s5, s5, 0x160
	s_add_i32 s4, s4, s5
	s_mul_hi_u32 s5, s4, 0x1745d18
	s_mul_i32 s13, s5, 0xb0
	s_sub_i32 s13, s4, s13
	s_and_b32 s13, s13, 7
	s_lshl_b32 s5, s5, 3
	s_add_i32 s5, s5, s13
	v_lshl_or_b32 v30, s5, 8, v5
	v_lshlrev_b32_e32 v30, 6, v30
	s_add_i32 s10, s10, s11
	global_load_dwordx4 v[96:99], v30, s[8:9]
	global_load_dwordx4 v[100:103], v30, s[8:9] offset:16
	global_load_dwordx4 v[104:107], v30, s[8:9] offset:32
	global_load_dwordx4 v[108:111], v30, s[8:9] offset:48
	s_cmp_lt_u32 s10, 0xb00
	s_cselect_b32 s4, s10, s2
	s_and_b32 s5, s4, 7
	s_lshr_b32 s4, s4, 3
	s_mul_i32 s5, s5, 0x160
	s_add_i32 s4, s4, s5
	s_mul_hi_u32 s5, s4, 0x1745d18
	s_mul_i32 s13, s5, 0xb0
	s_sub_i32 s13, s4, s13
	s_and_b32 s13, s13, 7
	s_lshl_b32 s5, s5, 3
	s_add_i32 s5, s5, s13
	v_lshl_or_b32 v31, s5, 8, v5
	v_lshlrev_b32_e32 v31, 6, v31
	s_add_i32 s10, s10, s11
	global_load_dwordx4 v[112:115], v31, s[8:9]
	global_load_dwordx4 v[116:119], v31, s[8:9] offset:16
	global_load_dwordx4 v[120:123], v31, s[8:9] offset:32
	global_load_dwordx4 v[124:127], v31, s[8:9] offset:48
	s_waitcnt vmcnt(20)
	v_add_f32_e32 v9, v32, v33
	v_add_f32_e32 v13, v34, v35
	v_add_f32_e32 v9, v9, v13
	v_add_f32_e32 v10, v36, v37
	v_add_f32_e32 v13, v38, v39
	v_add_f32_e32 v10, v10, v13
	v_add_f32_e32 v11, v40, v41
	v_add_f32_e32 v13, v42, v43
	v_add_f32_e32 v11, v11, v13
	v_add_f32_e32 v12, v44, v45
	v_add_f32_e32 v13, v46, v47
	v_add_f32_e32 v12, v12, v13
	v_add_f32_e32 v9, v9, v10
	v_add_f32_e32 v9, v9, v11
	v_add_f32_e32 v9, v9, v12
	v_fmamk_f32 v9, v9, 0x3a800000, v3
	v_mul_f32_e32 v10, 0x4f800000, v9
	v_cmp_gt_f32_e32 vcc, s16, v9
	s_nop 1
	v_cndmask_b32_e32 v9, v9, v10, vcc
	v_sqrt_f32_e32 v10, v9
	s_nop 0
	v_add_u32_e32 v11, -1, v10
	v_add_u32_e32 v12, 1, v10
	v_fma_f32 v13, -v11, v10, v9
	v_fma_f32 v14, -v12, v10, v9
	v_cmp_ge_f32_e64 s[4:5], 0, v13
	s_nop 1
	v_cndmask_b32_e64 v10, v10, v11, s[4:5]
	v_cmp_lt_f32_e64 s[4:5], 0, v14
	s_nop 1
	v_cndmask_b32_e64 v10, v10, v12, s[4:5]
	v_mul_f32_e32 v11, 0x37800000, v10
	v_cndmask_b32_e32 v10, v10, v11, vcc
	v_cmp_class_f32_e32 vcc, v9, v4
	s_nop 1
	v_cndmask_b32_e32 v9, v10, v9, vcc
	v_div_scale_f32 v10, s[4:5], v9, v9, 1.0
	v_rcp_f32_e32 v11, v10
	v_div_scale_f32 v12, vcc, 1.0, v9, 1.0
	v_fma_f32 v13, -v10, v11, 1.0
	v_fmac_f32_e32 v11, v13, v11
	v_mul_f32_e32 v13, v12, v11
	v_fma_f32 v14, -v10, v13, v12
	v_fmac_f32_e32 v13, v14, v11
	v_fma_f32 v10, -v10, v13, v12
	v_div_fmas_f32 v10, v10, v11, v13
	v_div_fixup_f32 v9, v10, v9, 1.0
	ds_write_b32 v2, v9
	s_waitcnt vmcnt(16)
; #define LAS __attribute__((address_space(3)))
; __device__ __forceinline__ float rowscale(const float* SS, int row) {
;     const f32x4* p = (const f32x4*)(SS + (size_t)row * 16);
;     const f32x4 a = p[0], b = p[1], c = p[2], d = p[3];
;     const float s = ((a[0] + a[1]) + (a[2] + a[3])) + ((b[0] + b[1]) + (b[2] + b[3])) + ((c[0] + c[1]) + (c[2] + c[3])) + ((d[0] + d[1]) + (d[2] + d[3]));
;     return 1.0f / sqrtf(s * (1.0f / 1024.0f) + 1e-6f);
; }
; DI void fill_rowscales(const pg8::StaticOrder& S, const float* SS, LAS float* rs, int bycol) {
;     pg8::Unit u;
;     for (int ui = 0; ui < RS_SLOTS && S.next(ui, u); ++ui) {
;         const int t = threadIdx.x;
;         if (t < 256) rs[ui * 256 + t] = pg8::rowscale(SS, (bycol ? u.pn : u.pm) * 256 + t);
;     }
	v_add_f32_e32 v9, v48, v49
	v_add_f32_e32 v13, v50, v51
	v_add_f32_e32 v9, v9, v13
	v_add_f32_e32 v10, v52, v53
	v_add_f32_e32 v13, v54, v55
	v_add_f32_e32 v10, v10, v13
	v_add_f32_e32 v11, v56, v57
	v_add_f32_e32 v13, v58, v59
	v_add_f32_e32 v11, v11, v13
	v_add_f32_e32 v12, v60, v61
	v_add_f32_e32 v13, v62, v63
	v_add_f32_e32 v12, v12, v13
	v_add_f32_e32 v9, v9, v10
	v_add_f32_e32 v9, v9, v11
	v_add_f32_e32 v9, v9, v12
	v_fmamk_f32 v9, v9, 0x3a800000, v3
	v_mul_f32_e32 v10, 0x4f800000, v9
	v_cmp_gt_f32_e32 vcc, s16, v9
	s_nop 1
	v_cndmask_b32_e32 v9, v9, v10, vcc
	v_sqrt_f32_e32 v10, v9
	s_nop 0
	v_add_u32_e32 v11, -1, v10
	v_add_u32_e32 v12, 1, v10
	v_fma_f32 v13, -v11, v10, v9
	v_fma_f32 v14, -v12, v10, v9
	v_cmp_ge_f32_e64 s[4:5], 0, v13
	s_nop 1
	v_cndmask_b32_e64 v10, v10, v11, s[4:5]
	v_cmp_lt_f32_e64 s[4:5], 0, v14
	s_nop 1
	v_cndmask_b32_e64 v10, v10, v12, s[4:5]
	v_mul_f32_e32 v11, 0x37800000, v10
	v_cndmask_b32_e32 v10, v10, v11, vcc
	v_cmp_class_f32_e32 vcc, v9, v4
	s_nop 1
	v_cndmask_b32_e32 v9, v10, v9, vcc
	v_div_scale_f32 v10, s[4:5], v9, v9, 1.0
	v_rcp_f32_e32 v11, v10
	v_div_scale_f32 v12, vcc, 1.0, v9, 1.0
	v_fma_f32 v13, -v10, v11, 1.0
	v_fmac_f32_e32 v11, v13, v11
	v_mul_f32_e32 v13, v12, v11
	v_fma_f32 v14, -v10, v13, v12
	v_fmac_f32_e32 v13, v14, v11
	v_fma_f32 v10, -v10, v13, v12
	v_div_fmas_f32 v10, v10, v11, v13
	v_div_fixup_f32 v9, v10, v9, 1.0
	ds_write_b32 v2, v9 offset:2048
	s_waitcnt vmcnt(12)
	v_add_f32_e32 v9, v64, v65
	v_add_f32_e32 v13, v66, v67
	v_add_f32_e32 v9, v9, v13
	v_add_f32_e32 v10, v68, v69
	v_add_f32_e32 v13, v70, v71
	v_add_f32_e32 v10, v10, v13
	v_add_f32_e32 v11, v72, v73
	v_add_f32_e32 v13, v74, v75
	v_add_f32_e32 v11, v11, v13
	v_add_f32_e32 v12, v76, v77
	v_add_f32_e32 v13, v78, v79
	v_add_f32_e32 v12, v12, v13
	v_add_f32_e32 v9, v9, v10
	v_add_f32_e32 v9, v9, v11
	v_add_f32_e32 v9, v9, v12
	v_fmamk_f32 v9, v9, 0x3a800000, v3
	v_mul_f32_e32 v10, 0x4f800000, v9
	v_cmp_gt_f32_e32 vcc, s16, v9
	s_nop 1
	v_cndmask_b32_e32 v9, v9, v10, vcc
	v_sqrt_f32_e32 v10, v9
	s_nop 0
	v_add_u32_e32 v11, -1, v10
	v_add_u32_e32 v12, 1, v10
	v_fma_f32 v13, -v11, v10, v9
	v_fma_f32 v14, -v12, v10, v9
	v_cmp_ge_f32_e64 s[4:5], 0, v13
	s_nop 1
	v_cndmask_b32_e64 v10, v10, v11, s[4:5]
	v_cmp_lt_f32_e64 s[4:5], 0, v14
	s_nop 1
	v_cndmask_b32_e64 v10, v10, v12, s[4:5]
	v_mul_f32_e32 v11, 0x37800000, v10
	v_cndmask_b32_e32 v10, v10, v11, vcc
	v_cmp_class_f32_e32 vcc, v9, v4
	s_nop 1
	v_cndmask_b32_e32 v9, v10, v9, vcc
	v_div_scale_f32 v10, s[4:5], v9, v9, 1.0
	v_rcp_f32_e32 v11, v10
	v_div_scale_f32 v12, vcc, 1.0, v9, 1.0
	v_fma_f32 v13, -v10, v11, 1.0
	v_fmac_f32_e32 v11, v13, v11
	v_mul_f32_e32 v13, v12, v11
	v_fma_f32 v14, -v10, v13, v12
	v_fmac_f32_e32 v13, v14, v11
	v_fma_f32 v10, -v10, v13, v12
	v_div_fmas_f32 v10, v10, v11, v13
	v_div_fixup_f32 v9, v10, v9, 1.0
	ds_write_b32 v2, v9 offset:4096
	s_waitcnt vmcnt(8)
	v_add_f32_e32 v9, v80, v81
	v_add_f32_e32 v13, v82, v83
	v_add_f32_e32 v9, v9, v13
	v_add_f32_e32 v10, v84, v85
	v_add_f32_e32 v13, v86, v87
	v_add_f32_e32 v10, v10, v13
	v_add_f32_e32 v11, v88, v89
	v_add_f32_e32 v13, v90, v91
	v_add_f32_e32 v11, v11, v13
	v_add_f32_e32 v12, v92, v93
	v_add_f32_e32 v13, v94, v95
	v_add_f32_e32 v12, v12, v13
	v_add_f32_e32 v9, v9, v10
	v_add_f32_e32 v9, v9, v11
	v_add_f32_e32 v9, v9, v12
	v_fmamk_f32 v9, v9, 0x3a800000, v3
	v_mul_f32_e32 v10, 0x4f800000, v9
	v_cmp_gt_f32_e32 vcc, s16, v9
	s_nop 1
	v_cndmask_b32_e32 v9, v9, v10, vcc
	v_sqrt_f32_e32 v10, v9
	s_nop 0
	v_add_u32_e32 v11, -1, v10
	v_add_u32_e32 v12, 1, v10
	v_fma_f32 v13, -v11, v10, v9
	v_fma_f32 v14, -v12, v10, v9
	v_cmp_ge_f32_e64 s[4:5], 0, v13
	s_nop 1
	v_cndmask_b32_e64 v10, v10, v11, s[4:5]
	v_cmp_lt_f32_e64 s[4:5], 0, v14
	s_nop 1
	v_cndmask_b32_e64 v10, v10, v12, s[4:5]
	v_mul_f32_e32 v11, 0x37800000, v10
	v_cndmask_b32_e32 v10, v10, v11, vcc
	v_cmp_class_f32_e32 vcc, v9, v4
	s_nop 1
	v_cndmask_b32_e32 v9, v10, v9, vcc
	v_div_scale_f32 v10, s[4:5], v9, v9, 1.0
	v_rcp_f32_e32 v11, v10
	v_div_scale_f32 v12, vcc, 1.0, v9, 1.0
	v_fma_f32 v13, -v10, v11, 1.0
	v_fmac_f32_e32 v11, v13, v11
	v_mul_f32_e32 v13, v12, v11
	v_fma_f32 v14, -v10, v13, v12
	v_fmac_f32_e32 v13, v14, v11
	v_fma_f32 v10, -v10, v13, v12
	v_div_fmas_f32 v10, v10, v11, v13
	v_div_fixup_f32 v9, v10, v9, 1.0
	ds_write_b32 v2, v9 offset:6144
	s_waitcnt vmcnt(4)
; #define LAS __attribute__((address_space(3)))
; __device__ __forceinline__ float rowscale(const float* SS, int row) {
;     const f32x4* p = (const f32x4*)(SS + (size_t)row * 16);
;     const f32x4 a = p[0], b = p[1], c = p[2], d = p[3];
;     const float s = ((a[0] + a[1]) + (a[2] + a[3])) + ((b[0] + b[1]) + (b[2] + b[3])) + ((c[0] + c[1]) + (c[2] + c[3])) + ((d[0] + d[1]) + (d[2] + d[3]));
;     return 1.0f / sqrtf(s * (1.0f / 1024.0f) + 1e-6f);
; }
; DI void fill_rowscales(const pg8::StaticOrder& S, const float* SS, LAS float* rs, int bycol) {
;     pg8::Unit u;
;     for (int ui = 0; ui < RS_SLOTS && S.next(ui, u); ++ui) {
;         const int t = threadIdx.x;
;         if (t < 256) rs[ui * 256 + t] = pg8::rowscale(SS, (bycol ? u.pn : u.pm) * 256 + t);
;     }
	v_add_f32_e32 v9, v96, v97
	v_add_f32_e32 v13, v98, v99
	v_add_f32_e32 v9, v9, v13
	v_add_f32_e32 v10, v100, v101
	v_add_f32_e32 v13, v102, v103
	v_add_f32_e32 v10, v10, v13
	v_add_f32_e32 v11, v104, v105
	v_add_f32_e32 v13, v106, v107
	v_add_f32_e32 v11, v11, v13
	v_add_f32_e32 v12, v108, v109
	v_add_f32_e32 v13, v110, v111
	v_add_f32_e32 v12, v12, v13
	v_add_f32_e32 v9, v9, v10
	v_add_f32_e32 v9, v9, v11
	v_add_f32_e32 v9, v9, v12
	v_fmamk_f32 v9, v9, 0x3a800000, v3
	v_mul_f32_e32 v10, 0x4f800000, v9
	v_cmp_gt_f32_e32 vcc, s16, v9
	s_nop 1
	v_cndmask_b32_e32 v9, v9, v10, vcc
	v_sqrt_f32_e32 v10, v9
	s_nop 0
	v_add_u32_e32 v11, -1, v10
	v_add_u32_e32 v12, 1, v10
	v_fma_f32 v13, -v11, v10, v9
	v_fma_f32 v14, -v12, v10, v9
	v_cmp_ge_f32_e64 s[4:5], 0, v13
	s_nop 1
	v_cndmask_b32_e64 v10, v10, v11, s[4:5]
	v_cmp_lt_f32_e64 s[4:5], 0, v14
	s_nop 1
	v_cndmask_b32_e64 v10, v10, v12, s[4:5]
	v_mul_f32_e32 v11, 0x37800000, v10
	v_cndmask_b32_e32 v10, v10, v11, vcc
	v_cmp_class_f32_e32 vcc, v9, v4
	s_nop 1
	v_cndmask_b32_e32 v9, v10, v9, vcc
	v_div_scale_f32 v10, s[4:5], v9, v9, 1.0
	v_rcp_f32_e32 v11, v10
	v_div_scale_f32 v12, vcc, 1.0, v9, 1.0
	v_fma_f32 v13, -v10, v11, 1.0
	v_fmac_f32_e32 v11, v13, v11
	v_mul_f32_e32 v13, v12, v11
	v_fma_f32 v14, -v10, v13, v12
	v_fmac_f32_e32 v13, v14, v11
	v_fma_f32 v10, -v10, v13, v12
	v_div_fmas_f32 v10, v10, v11, v13
	v_div_fixup_f32 v9, v10, v9, 1.0
	ds_write_b32 v2, v9 offset:8192
	s_waitcnt vmcnt(0)
	v_add_f32_e32 v9, v112, v113
	v_add_f32_e32 v13, v114, v115
	v_add_f32_e32 v9, v9, v13
	v_add_f32_e32 v10, v116, v117
	v_add_f32_e32 v13, v118, v119
	v_add_f32_e32 v10, v10, v13
	v_add_f32_e32 v11, v120, v121
	v_add_f32_e32 v13, v122, v123
	v_add_f32_e32 v11, v11, v13
	v_add_f32_e32 v12, v124, v125
	v_add_f32_e32 v13, v126, v127
	v_add_f32_e32 v12, v12, v13
	v_add_f32_e32 v9, v9, v10
	v_add_f32_e32 v9, v9, v11
	v_add_f32_e32 v9, v9, v12
	v_fmamk_f32 v9, v9, 0x3a800000, v3
	v_mul_f32_e32 v10, 0x4f800000, v9
	v_cmp_gt_f32_e32 vcc, s16, v9
	s_nop 1
	v_cndmask_b32_e32 v9, v9, v10, vcc
	v_sqrt_f32_e32 v10, v9
	s_nop 0
	v_add_u32_e32 v11, -1, v10
	v_add_u32_e32 v12, 1, v10
	v_fma_f32 v13, -v11, v10, v9
	v_fma_f32 v14, -v12, v10, v9
	v_cmp_ge_f32_e64 s[4:5], 0, v13
	s_nop 1
	v_cndmask_b32_e64 v10, v10, v11, s[4:5]
	v_cmp_lt_f32_e64 s[4:5], 0, v14
	s_nop 1
	v_cndmask_b32_e64 v10, v10, v12, s[4:5]
	v_mul_f32_e32 v11, 0x37800000, v10
	v_cndmask_b32_e32 v10, v10, v11, vcc
	v_cmp_class_f32_e32 vcc, v9, v4
	s_nop 1
	v_cndmask_b32_e32 v9, v10, v9, vcc
	v_div_scale_f32 v10, s[4:5], v9, v9, 1.0
	v_rcp_f32_e32 v11, v10
	v_div_scale_f32 v12, vcc, 1.0, v9, 1.0
	v_fma_f32 v13, -v10, v11, 1.0
	v_fmac_f32_e32 v11, v13, v11
	v_mul_f32_e32 v13, v12, v11
	v_fma_f32 v14, -v10, v13, v12
	v_fmac_f32_e32 v13, v14, v11
	v_fma_f32 v10, -v10, v13, v12
	v_div_fmas_f32 v10, v10, v11, v13
	v_div_fixup_f32 v9, v10, v9, 1.0
	ds_write_b32 v2, v9 offset:10240
